# v20 + attention: shared softmax bound max(mb0,mb1) so far-block accumulator init is one loop-invariant SrcC quad (16 fewer VALU per far half-block)
# speedup vs baseline: 1.0028x; 1.0028x over previous
.LBB0_138:
	v_add_f32_e32 v0, v0, v54
	s_mov_b32 s6, 0xf800000
	v_mul_f32_e32 v2, 0x4f800000, v0
	v_cmp_gt_f32_e32 vcc, s6, v0
	s_waitcnt lgkmcnt(0)
	s_barrier
	v_cndmask_b32_e32 v0, v0, v2, vcc
	v_sqrt_f32_e32 v2, v0
	ds_read_b64 v[170:171], v1 offset:512
	s_lshl_b32 s41, s10, 1
	v_add_u32_e32 v3, -1, v2
	v_fma_f32 v53, -v3, v2, v0
	v_add_u32_e32 v52, 1, v2
	v_cmp_ge_f32_e64 s[44:45], 0, v53
	v_subrev_u32_e32 v209, 64, v207
	s_add_i32 s51, s41, 2
	v_cndmask_b32_e64 v3, v2, v3, s[44:45]
	v_fma_f32 v2, -v52, v2, v0
	v_cmp_lt_f32_e64 s[44:45], 0, v2
	v_add_u32_e32 v159, 0xffffff81, v163
	v_or_b32_e32 v161, 15, v163
	v_cndmask_b32_e64 v2, v3, v52, s[44:45]
	v_add_f32_e32 v52, v55, v56
	v_mul_f32_e32 v53, 0x4f800000, v52
	v_cmp_gt_f32_e64 s[44:45], s6, v52
	v_mul_f32_e32 v3, 0x37800000, v2
	v_cndmask_b32_e32 v2, v2, v3, vcc
	v_cndmask_b32_e64 v52, v52, v53, s[44:45]
	v_sqrt_f32_e32 v53, v52
	v_cmp_class_f32_e32 vcc, v0, v180
	v_subrev_u32_e32 v208, 49, v163
	v_add_u32_e32 v210, v209, v197
	v_cndmask_b32_e32 v0, v2, v0, vcc
	v_add_u32_e32 v2, -1, v53
	v_fma_f32 v3, -v2, v53, v52
	v_cmp_ge_f32_e32 vcc, 0, v3
	v_add_u32_e32 v3, 1, v53
	s_waitcnt lgkmcnt(0)
	v_fma_f32 v120, v192, v0, v171
	v_cndmask_b32_e32 v2, v53, v2, vcc
	v_fma_f32 v53, -v3, v53, v52
	v_cmp_lt_f32_e32 vcc, 0, v53
	v_mov_b32_e32 v0, v1
	v_add_u32_e32 v211, v145, v209
	v_cndmask_b32_e32 v2, v2, v3, vcc
	v_mul_f32_e32 v3, 0x37800000, v2
	v_cndmask_b32_e64 v2, v2, v3, s[44:45]
	v_cmp_class_f32_e32 vcc, v52, v180
	v_mov_b32_e32 v3, v1
	v_add_u32_e32 v212, v198, v209
	v_cndmask_b32_e32 v2, v2, v52, vcc
	v_fma_f32 v122, v192, v2, v171
	v_mov_b32_e32 v2, v1
	v_mov_b64_e32 v[106:107], v[2:3]
	v_mov_b64_e32 v[102:103], v[2:3]
	v_mov_b64_e32 v[90:91], v[2:3]
	v_mov_b64_e32 v[86:87], v[2:3]
	v_mov_b64_e32 v[74:75], v[2:3]
	v_mov_b64_e32 v[70:71], v[2:3]
	v_mov_b64_e32 v[58:59], v[2:3]
	v_mov_b64_e32 v[54:55], v[2:3]
	v_mov_b64_e32 v[114:115], v[2:3]
	v_mov_b64_e32 v[110:111], v[2:3]
	v_mov_b64_e32 v[98:99], v[2:3]
	v_mov_b64_e32 v[94:95], v[2:3]
	v_mov_b64_e32 v[82:83], v[2:3]
	v_mov_b64_e32 v[78:79], v[2:3]
	v_mov_b64_e32 v[66:67], v[2:3]
	v_mov_b64_e32 v[62:63], v[2:3]
	v_mov_b64_e32 v[118:119], v[2:3]
	v_mov_b64_e32 v[130:131], v[2:3]
	v_add_u32_e32 v213, v199, v209
	v_add_u32_e32 v214, v200, v209
	v_add_u32_e32 v215, v201, v209
	v_add_u32_e32 v216, v202, v209
	v_max_f32_e32 v120, v120, v122
	v_mov_b32_e32 v122, v120
	v_sub_f32_e32 v252, v170, v120
	v_mov_b32_e32 v253, v252
	v_mov_b32_e32 v254, v252
	v_mov_b32_e32 v255, v252
	v_mov_b32_e32 v121, v120
	v_mov_b32_e32 v124, v120
	v_mov_b32_e32 v123, v120
	v_mov_b32_e32 v125, v122
	v_mov_b32_e32 v126, v122
	v_mov_b32_e32 v127, v122
	s_mov_b32 s57, 0
	v_mov_b64_e32 v[104:105], v[0:1]
	v_mov_b64_e32 v[100:101], v[0:1]
	v_mov_b64_e32 v[88:89], v[0:1]
	v_mov_b64_e32 v[84:85], v[0:1]
	v_mov_b64_e32 v[72:73], v[0:1]
	v_mov_b64_e32 v[68:69], v[0:1]
	v_mov_b64_e32 v[56:57], v[0:1]
	v_mov_b64_e32 v[52:53], v[0:1]
	v_mov_b64_e32 v[112:113], v[0:1]
	v_mov_b64_e32 v[108:109], v[0:1]
	v_mov_b64_e32 v[96:97], v[0:1]
	v_mov_b64_e32 v[92:93], v[0:1]
	v_mov_b64_e32 v[80:81], v[0:1]
	v_mov_b64_e32 v[76:77], v[0:1]
	v_mov_b64_e32 v[64:65], v[0:1]
	v_mov_b64_e32 v[60:61], v[0:1]
	v_mov_b64_e32 v[116:117], v[0:1]
	v_mov_b64_e32 v[128:129], v[0:1]
	s_branch .LBB0_140

.Lfar_a:
	s_or_b64 exec, exec, s[12:13]
	s_lshl_b32 s13, s29, 6
	s_mul_i32 s12, s29, 0x2200
	s_add_i32 s13, s13, 0
	v_add_u32_e32 v171, s12, v139
	ds_read_b128 v[222:225], v171 offset:1024
	ds_read_b128 v[226:229], v171 offset:1088
	ds_read_b128 v[230:233], v171 offset:2112
	ds_read_b128 v[234:237], v171 offset:2176
	s_waitcnt lgkmcnt(4)
	s_waitcnt lgkmcnt(3)
	v_mfma_f32_16x16x32_bf16 v[222:225], v[222:225], v[4:7], v[252:255]
	s_waitcnt lgkmcnt(1)
	v_mfma_f32_16x16x32_bf16 v[230:233], v[230:233], v[4:7], v[252:255]
	v_mfma_f32_16x16x32_bf16 v[222:225], v[226:229], v[8:11], v[222:225]
	ds_read_b128 v[226:229], v171 offset:1152
	ds_read_b128 v[238:241], v171 offset:1216
	s_waitcnt lgkmcnt(2)
	v_mfma_f32_16x16x32_bf16 v[230:233], v[234:237], v[8:11], v[230:233]
	ds_read_b128 v[234:237], v171 offset:2240
	ds_read_b128 v[242:245], v171 offset:2304
	s_nop 2
	v_exp_f32_e32 v3, v223
	v_exp_f32_e32 v219, v225
	s_waitcnt lgkmcnt(3)
	v_mfma_f32_16x16x32_bf16 v[226:229], v[226:229], v[12:15], v[252:255]
	v_exp_f32_e32 v225, v231
	s_nop 1
	s_waitcnt lgkmcnt(2)
	v_mfma_f32_16x16x32_bf16 v[226:229], v[238:241], v[16:19], v[226:229]
	v_add3_u32 v0, s13, v134, v135
	v_exp_f32_e32 v217, v224
	s_waitcnt lgkmcnt(1)
	v_mfma_f32_16x16x32_bf16 v[172:175], v[234:237], v[12:15], v[252:255]
	ds_read_b128 v[234:237], v0 offset:18432
	ds_read_b128 v[238:241], v0 offset:20736
	s_nop 1
	v_exp_f32_e32 v2, v226
	v_exp_f32_e32 v171, v227
	s_waitcnt lgkmcnt(2)
	v_mfma_f32_16x16x32_bf16 v[172:175], v[242:245], v[16:19], v[172:175]
	ds_read_b128 v[242:245], v0 offset:23040
	ds_read_b128 v[246:249], v0 offset:25344
	v_exp_f32_e32 v0, v222
	v_exp_f32_e32 v218, v228
	v_exp_f32_e32 v223, v229
	v_exp_f32_e32 v222, v230
	s_nop 1
	v_exp_f32_e32 v224, v172
	v_exp_f32_e32 v226, v173
	v_exp_f32_e32 v227, v232
	v_exp_f32_e32 v228, v174
	v_exp_f32_e32 v229, v233
	v_exp_f32_e32 v230, v175
	v_cvt_pk_bf16_f32 v172, v0, v3
	v_cvt_pk_bf16_f32 v173, v217, v219
	v_cvt_pk_bf16_f32 v174, v222, v225
	v_cvt_pk_bf16_f32 v175, v227, v229
	v_cvt_pk_bf16_f32 v222, v2, v171
	v_cvt_pk_bf16_f32 v223, v218, v223
	v_cvt_pk_bf16_f32 v224, v224, v226
	v_cvt_pk_bf16_f32 v225, v228, v230
	v_add3_u32 v0, s13, v135, v134
	s_waitcnt lgkmcnt(3)
	v_mfma_f32_16x16x32_bf16 v[104:107], v[234:237], v[172:175], v[104:107]
	ds_read_b128 v[226:229], v0 offset:27648
	ds_read_b128 v[230:233], v0 offset:29952
	v_mfma_f32_16x16x32_bf16 v[112:115], v[234:237], v[222:225], v[112:115]
	ds_read_b128 v[234:237], v0 offset:32256
	s_waitcnt lgkmcnt(5)
	v_mfma_f32_16x16x32_bf16 v[100:103], v[238:241], v[172:175], v[100:103]
	v_mfma_f32_16x16x32_bf16 v[108:111], v[238:241], v[222:225], v[108:111]
	ds_read_b128 v[238:241], v0 offset:34560
	s_waitcnt lgkmcnt(5)
	v_mfma_f32_16x16x32_bf16 v[88:91], v[242:245], v[172:175], v[88:91]
	v_mfma_f32_16x16x32_bf16 v[96:99], v[242:245], v[222:225], v[96:99]
	s_waitcnt lgkmcnt(4)
	v_mfma_f32_16x16x32_bf16 v[84:87], v[246:249], v[172:175], v[84:87]
	v_mfma_f32_16x16x32_bf16 v[92:95], v[246:249], v[222:225], v[92:95]
	s_mov_b32 s66, s64
	s_mov_b32 s67, s64
	s_waitcnt lgkmcnt(3)
	v_mfma_f32_16x16x32_bf16 v[72:75], v[226:229], v[172:175], v[72:75]
	s_mov_b32 s65, s64
	v_mfma_f32_16x16x32_bf16 v[80:83], v[226:229], v[222:225], v[80:83]
	v_mov_b64_e32 v[228:229], s[66:67]
	v_mov_b64_e32 v[226:227], s[64:65]
	s_waitcnt lgkmcnt(2)
	v_mfma_f32_16x16x32_bf16 v[68:71], v[230:233], v[172:175], v[68:71]
	v_mfma_f32_16x16x32_bf16 v[76:79], v[230:233], v[222:225], v[76:79]
	s_waitcnt lgkmcnt(1)
	v_mfma_f32_16x16x32_bf16 v[56:59], v[234:237], v[172:175], v[56:59]
	v_mfma_f32_16x16x32_bf16 v[64:67], v[234:237], v[222:225], v[64:67]
	s_waitcnt lgkmcnt(0)
	v_mfma_f32_16x16x32_bf16 v[52:55], v[238:241], v[172:175], v[52:55]
	v_mfma_f32_16x16x32_bf16 v[60:63], v[238:241], v[222:225], v[60:63]
	v_mfma_f32_16x16x32_bf16 v[128:131], v[226:229], v[172:175], v[128:131]
	v_mfma_f32_16x16x32_bf16 v[116:119], v[226:229], v[222:225], v[116:119]
	s_branch .LBB0_142

.LBB0_162:
	s_andn2_saveexec_b64 s[12:13], s[12:13]
	s_cbranch_execz .LBB0_141
	s_cmp_eq_u64 s[12:13], 0
	s_cbranch_scc1 .Lfar_a
	s_waitcnt lgkmcnt(0)
	v_mov_b32_e32 v0, v170
	v_mov_b32_e32 v217, v170
	s_branch .LBB0_141

.Lfar_b:
	s_or_b64 exec, exec, s[12:13]
	s_lshl_b32 s13, s29, 6
	s_mul_i32 s12, s29, 0x2200
	s_add_i32 s13, s13, 0
	v_add_u32_e32 v171, s12, v139
	ds_read_b128 v[222:225], v171 offset:36864
	ds_read_b128 v[226:229], v171 offset:36928
	ds_read_b128 v[230:233], v171 offset:37952
	ds_read_b128 v[234:237], v171 offset:38016
	s_waitcnt lgkmcnt(4)
	s_waitcnt lgkmcnt(3)
	v_mfma_f32_16x16x32_bf16 v[222:225], v[222:225], v[4:7], v[252:255]
	s_waitcnt lgkmcnt(1)
	v_mfma_f32_16x16x32_bf16 v[230:233], v[230:233], v[4:7], v[252:255]
	v_mfma_f32_16x16x32_bf16 v[222:225], v[226:229], v[8:11], v[222:225]
	ds_read_b128 v[226:229], v171 offset:36992
	ds_read_b128 v[238:241], v171 offset:37056
	s_waitcnt lgkmcnt(2)
	v_mfma_f32_16x16x32_bf16 v[230:233], v[234:237], v[8:11], v[230:233]
	ds_read_b128 v[234:237], v171 offset:38080
	ds_read_b128 v[242:245], v171 offset:38144
	s_nop 2
	v_exp_f32_e32 v3, v223
	v_exp_f32_e32 v219, v225
	s_waitcnt lgkmcnt(3)
	v_mfma_f32_16x16x32_bf16 v[226:229], v[226:229], v[12:15], v[252:255]
	v_exp_f32_e32 v225, v231
	s_nop 1
	s_waitcnt lgkmcnt(2)
	v_mfma_f32_16x16x32_bf16 v[226:229], v[238:241], v[16:19], v[226:229]
	v_add3_u32 v0, s13, v134, v135
	v_exp_f32_e32 v217, v224
	s_waitcnt lgkmcnt(1)
	v_mfma_f32_16x16x32_bf16 v[172:175], v[234:237], v[12:15], v[252:255]
	ds_read_b128 v[234:237], v0 offset:54272
	ds_read_b128 v[238:241], v0 offset:56576
	s_nop 1
	v_exp_f32_e32 v2, v226
	v_exp_f32_e32 v171, v227
	s_waitcnt lgkmcnt(2)
	v_mfma_f32_16x16x32_bf16 v[172:175], v[242:245], v[16:19], v[172:175]
	ds_read_b128 v[242:245], v0 offset:58880
	ds_read_b128 v[246:249], v0 offset:61184
	v_exp_f32_e32 v0, v222
	v_exp_f32_e32 v218, v228
	v_exp_f32_e32 v223, v229
	v_exp_f32_e32 v222, v230
	s_nop 1
	v_exp_f32_e32 v224, v172
	v_exp_f32_e32 v226, v173
	v_exp_f32_e32 v227, v232
	v_exp_f32_e32 v228, v174
	v_exp_f32_e32 v229, v233
	v_exp_f32_e32 v230, v175
	v_cvt_pk_bf16_f32 v172, v0, v3
	v_cvt_pk_bf16_f32 v173, v217, v219
	v_cvt_pk_bf16_f32 v174, v222, v225
	v_cvt_pk_bf16_f32 v175, v227, v229
	v_cvt_pk_bf16_f32 v222, v2, v171
	v_cvt_pk_bf16_f32 v223, v218, v223
	v_cvt_pk_bf16_f32 v224, v224, v226
	v_cvt_pk_bf16_f32 v225, v228, v230
	v_add3_u32 v0, s13, v135, v134
	v_add_u32_e32 v2, 0x10100, v0
	ds_read_b128 v[226:229], v0 offset:63488
	ds_read_b128 v[230:233], v2
	v_add_u32_e32 v2, 0x10a00, v0
	v_add_u32_e32 v0, 0x11300, v0
	s_waitcnt lgkmcnt(5)
	v_mfma_f32_16x16x32_bf16 v[104:107], v[234:237], v[172:175], v[104:107]
	v_mfma_f32_16x16x32_bf16 v[112:115], v[234:237], v[222:225], v[112:115]
	ds_read_b128 v[234:237], v2
	s_waitcnt lgkmcnt(5)
	v_mfma_f32_16x16x32_bf16 v[100:103], v[238:241], v[172:175], v[100:103]
	v_mfma_f32_16x16x32_bf16 v[108:111], v[238:241], v[222:225], v[108:111]
	ds_read_b128 v[238:241], v0
	s_waitcnt lgkmcnt(5)
	v_mfma_f32_16x16x32_bf16 v[88:91], v[242:245], v[172:175], v[88:91]
	v_mfma_f32_16x16x32_bf16 v[96:99], v[242:245], v[222:225], v[96:99]
	s_waitcnt lgkmcnt(4)
	v_mfma_f32_16x16x32_bf16 v[84:87], v[246:249], v[172:175], v[84:87]
	v_mfma_f32_16x16x32_bf16 v[92:95], v[246:249], v[222:225], v[92:95]
	s_mov_b32 s66, s64
	s_mov_b32 s67, s64
	s_waitcnt lgkmcnt(3)
	v_mfma_f32_16x16x32_bf16 v[72:75], v[226:229], v[172:175], v[72:75]
	s_mov_b32 s65, s64
	v_mfma_f32_16x16x32_bf16 v[80:83], v[226:229], v[222:225], v[80:83]
	v_mov_b64_e32 v[228:229], s[66:67]
	v_mov_b64_e32 v[226:227], s[64:65]
	s_waitcnt lgkmcnt(2)
	v_mfma_f32_16x16x32_bf16 v[68:71], v[230:233], v[172:175], v[68:71]
	v_mfma_f32_16x16x32_bf16 v[76:79], v[230:233], v[222:225], v[76:79]
	s_waitcnt lgkmcnt(1)
	v_mfma_f32_16x16x32_bf16 v[56:59], v[234:237], v[172:175], v[56:59]
	v_mfma_f32_16x16x32_bf16 v[64:67], v[234:237], v[222:225], v[64:67]
	s_waitcnt lgkmcnt(0)
	v_mfma_f32_16x16x32_bf16 v[52:55], v[238:241], v[172:175], v[52:55]
	v_mfma_f32_16x16x32_bf16 v[60:63], v[238:241], v[222:225], v[60:63]
	v_mfma_f32_16x16x32_bf16 v[128:131], v[226:229], v[172:175], v[128:131]
	v_mfma_f32_16x16x32_bf16 v[116:119], v[226:229], v[222:225], v[116:119]
	s_branch .LBB0_168
